# grid barrier: the XCD leader that completes the barrier bumps every XCD's release word itself (one 16-lane atomic), other leaders no longer relay
# speedup vs baseline: 1.0059x; 1.0059x over previous
.Lxb_rel0:
	s_mov_b64 exec, 0xffff
	v_mbcnt_lo_u32_b32 v1, -1, 0
	v_lshlrev_b32_e32 v1, 8, v1
	v_add_u32_e32 v1, 0xc2400, v1
	v_mov_b32_e32 v2, 1
	global_atomic_add v1, v2, s[26:27]
	s_mov_b64 exec, 0

.LBB0_94:
	s_or_b64 exec, exec, s[0:1]
	s_mov_b64 s[0:1], exec
	v_mbcnt_lo_u32_b32 v0, s0, 0
	v_mbcnt_hi_u32_b32 v0, s1, v0
	v_cmp_eq_u32_e32 vcc, 0, v0
	buffer_inv sc1
	s_and_saveexec_b64 s[4:5], vcc
	s_cbranch_execz .LBB0_96
	s_bcnt1_i32_b64 s0, s[0:1]
	v_mov_b32_e32 v0, 0x2000
	v_mov_b32_e32 v1, s0

.LBB0_1803:
	s_or_b64 exec, exec, s[0:1]
	s_mov_b64 s[0:1], exec
	v_mbcnt_lo_u32_b32 v0, s0, 0
	v_mbcnt_hi_u32_b32 v0, s1, v0
	v_cmp_eq_u32_e32 vcc, 0, v0
	buffer_inv sc1
	s_and_saveexec_b64 s[8:9], vcc
	s_cbranch_execz .LBB0_1805
	s_bcnt1_i32_b64 s0, s[0:1]
	v_mov_b32_e32 v0, 0x2000
	v_mov_b32_e32 v1, s0
